# grid barriers: the last top-level arriver advances every XCD's generation word itself (16 fire-and-forget atomics) instead of each XCD leader relaying it after its own poll: one hop less for all waiti
# speedup vs baseline: 1.0103x; 1.0006x over previous
; __device__ __forceinline__ unsigned xb_ld(unsigned* p)              { return __hip_atomic_load(p, __ATOMIC_RELAXED, __HIP_MEMORY_SCOPE_AGENT); }
; __device__ __forceinline__ unsigned xb_add(unsigned* p, unsigned v) { return __hip_atomic_fetch_add(p, v, __ATOMIC_RELAXED, __HIP_MEMORY_SCOPE_AGENT); }
; #define XB_SPIN(cond, bar) do { unsigned _sp = 0; while (cond) { __builtin_amdgcn_s_sleep(1); \
;     if ((++_sp & 255u) == 0u) { if (xb_ld(&(bar)[XB_TMO])) break; if (_sp > XB_SPIN_CAP) { atomicAdd(&(bar)[XB_TMO], 1u); break; } } } } while (0)
; __device__ __forceinline__ void xcd_barrier(const XcdBarrier& b) {
;     ...
;         if (old + 1u == (gen + 1u) * nloc) {
;             __builtin_amdgcn_fence(__ATOMIC_RELEASE, "agent");
;             asm volatile("s_waitcnt vmcnt(0)" ::: "memory");
;             const unsigned og = xb_add(&bar[XB_TOP], 1u);
;             const unsigned tg = og / nx;
;             if (og + 1u == (tg + 1u) * nx) xb_add(&bar[XB_TOPGEN], 1u);
;             else XB_SPIN(xb_ld(&bar[XB_TOPGEN]) == tg, bar);
;             __builtin_amdgcn_fence(__ATOMIC_ACQUIRE, "agent");
;             xb_add(&bar[XB_XGEN(b.x)], 1u);
.LBB0_461:
	s_or_b64 exec, exec, s[8:9]
	v_readlane_b32 s8, v242, 30
	v_readlane_b32 s9, v242, 31
	s_nop 1
	v_mov_b64_e32 v[0:1], s[8:9]
	s_orn2_b64 s[8:9], s[10:11], exec
	s_branch .LBB0_462
.Lbar_last_0:
	s_or_b64 exec, exec, s[6:7]
	v_mov_b32_e32 v2, 1
	global_atomic_add v[0:1], v2, off
	v_add_co_u32_e32 v4, vcc, 0xffffef00, v0
	s_nop 1
	v_addc_co_u32_e32 v5, vcc, -1, v1, vcc
	global_atomic_add v[4:5], v2, off
	global_atomic_add v[4:5], v2, off offset:256
	global_atomic_add v[4:5], v2, off offset:512
	global_atomic_add v[4:5], v2, off offset:768
	global_atomic_add v[4:5], v2, off offset:1024
	global_atomic_add v[4:5], v2, off offset:1280
	global_atomic_add v[4:5], v2, off offset:1536
	global_atomic_add v[4:5], v2, off offset:1792
	global_atomic_add v[4:5], v2, off offset:2048
	global_atomic_add v[4:5], v2, off offset:2304
	global_atomic_add v[4:5], v2, off offset:2560
	global_atomic_add v[4:5], v2, off offset:2816
	global_atomic_add v[4:5], v2, off offset:3072
	global_atomic_add v[4:5], v2, off offset:3328
	global_atomic_add v[4:5], v2, off offset:3584
	global_atomic_add v[4:5], v2, off offset:3840
	s_mov_b64 s[8:9], 0

; __device__ __forceinline__ unsigned xb_add(unsigned* p, unsigned v) { return __hip_atomic_fetch_add(p, v, __ATOMIC_RELAXED, __HIP_MEMORY_SCOPE_AGENT); }
; __device__ __forceinline__ void xcd_barrier(const XcdBarrier& b) {
;     ...
;             __builtin_amdgcn_fence(__ATOMIC_ACQUIRE, "agent");
;             xb_add(&bar[XB_XGEN(b.x)], 1u);
;             asm volatile("s_waitcnt vmcnt(0)" ::: "memory");
.LBB0_464:
	s_or_b64 exec, exec, s[6:7]
	s_mov_b64 s[6:7], exec
	v_mbcnt_lo_u32_b32 v0, s6, 0
	v_mbcnt_hi_u32_b32 v0, s7, v0
	v_cmp_eq_u32_e32 vcc, 0, v0
	s_waitcnt vmcnt(0)
	s_and_saveexec_b64 s[8:9], vcc
	s_cbranch_execz .LBB0_466
	s_bcnt1_i32_b64 s6, s[6:7]
	v_mov_b32_e32 v0, 0
	v_mov_b32_e32 v1, s6
.LBB0_466:
	s_or_b64 exec, exec, s[8:9]
	s_waitcnt vmcnt(0)

; __device__ __forceinline__ unsigned xb_ld(unsigned* p)              { return __hip_atomic_load(p, __ATOMIC_RELAXED, __HIP_MEMORY_SCOPE_AGENT); }
; __device__ __forceinline__ unsigned xb_add(unsigned* p, unsigned v) { return __hip_atomic_fetch_add(p, v, __ATOMIC_RELAXED, __HIP_MEMORY_SCOPE_AGENT); }
; #define XB_SPIN(cond, bar) do { unsigned _sp = 0; while (cond) { __builtin_amdgcn_s_sleep(1); \
;     if ((++_sp & 255u) == 0u) { if (xb_ld(&(bar)[XB_TMO])) break; if (_sp > XB_SPIN_CAP) { atomicAdd(&(bar)[XB_TMO], 1u); break; } } } } while (0)
; __device__ __forceinline__ void xcd_barrier(const XcdBarrier& b) {
;     ...
;         if (old + 1u == (gen + 1u) * nloc) {
;             __builtin_amdgcn_fence(__ATOMIC_RELEASE, "agent");
;             asm volatile("s_waitcnt vmcnt(0)" ::: "memory");
;             const unsigned og = xb_add(&bar[XB_TOP], 1u);
;             const unsigned tg = og / nx;
;             if (og + 1u == (tg + 1u) * nx) xb_add(&bar[XB_TOPGEN], 1u);
;             else XB_SPIN(xb_ld(&bar[XB_TOPGEN]) == tg, bar);
;             __builtin_amdgcn_fence(__ATOMIC_ACQUIRE, "agent");
;             xb_add(&bar[XB_XGEN(b.x)], 1u);
.LBB0_635:
	s_or_b64 exec, exec, s[10:11]
	v_readlane_b32 s10, v242, 30
	v_readlane_b32 s11, v242, 31
	s_nop 1
	v_mov_b64_e32 v[0:1], s[10:11]
	s_orn2_b64 s[10:11], s[12:13], exec
	s_branch .LBB0_636
.Lbar_last_1:
	s_or_b64 exec, exec, s[8:9]
	v_mov_b32_e32 v2, 1
	global_atomic_add v[0:1], v2, off
	v_add_co_u32_e32 v4, vcc, 0xffffef00, v0
	s_nop 1
	v_addc_co_u32_e32 v5, vcc, -1, v1, vcc
	global_atomic_add v[4:5], v2, off
	global_atomic_add v[4:5], v2, off offset:256
	global_atomic_add v[4:5], v2, off offset:512
	global_atomic_add v[4:5], v2, off offset:768
	global_atomic_add v[4:5], v2, off offset:1024
	global_atomic_add v[4:5], v2, off offset:1280
	global_atomic_add v[4:5], v2, off offset:1536
	global_atomic_add v[4:5], v2, off offset:1792
	global_atomic_add v[4:5], v2, off offset:2048
	global_atomic_add v[4:5], v2, off offset:2304
	global_atomic_add v[4:5], v2, off offset:2560
	global_atomic_add v[4:5], v2, off offset:2816
	global_atomic_add v[4:5], v2, off offset:3072
	global_atomic_add v[4:5], v2, off offset:3328
	global_atomic_add v[4:5], v2, off offset:3584
	global_atomic_add v[4:5], v2, off offset:3840
	s_mov_b64 s[10:11], 0

; __device__ __forceinline__ unsigned xb_add(unsigned* p, unsigned v) { return __hip_atomic_fetch_add(p, v, __ATOMIC_RELAXED, __HIP_MEMORY_SCOPE_AGENT); }
; __device__ __forceinline__ void xcd_barrier(const XcdBarrier& b) {
;     ...
;             __builtin_amdgcn_fence(__ATOMIC_ACQUIRE, "agent");
;             xb_add(&bar[XB_XGEN(b.x)], 1u);
;             asm volatile("s_waitcnt vmcnt(0)" ::: "memory");
.LBB0_638:
	s_or_b64 exec, exec, s[8:9]
	s_mov_b64 s[8:9], exec
	v_mbcnt_lo_u32_b32 v0, s8, 0
	v_mbcnt_hi_u32_b32 v0, s9, v0
	v_cmp_eq_u32_e32 vcc, 0, v0
	s_waitcnt vmcnt(0)
	s_and_saveexec_b64 s[10:11], vcc
	s_cbranch_execz .LBB0_640
	s_bcnt1_i32_b64 s8, s[8:9]
	v_mov_b32_e32 v0, 0
	v_mov_b32_e32 v1, s8
.LBB0_640:
	s_or_b64 exec, exec, s[10:11]
	s_waitcnt vmcnt(0)

; __device__ __forceinline__ unsigned xb_ld(unsigned* p)              { return __hip_atomic_load(p, __ATOMIC_RELAXED, __HIP_MEMORY_SCOPE_AGENT); }
; __device__ __forceinline__ unsigned xb_add(unsigned* p, unsigned v) { return __hip_atomic_fetch_add(p, v, __ATOMIC_RELAXED, __HIP_MEMORY_SCOPE_AGENT); }
; #define XB_SPIN(cond, bar) do { unsigned _sp = 0; while (cond) { __builtin_amdgcn_s_sleep(1); \
;     if ((++_sp & 255u) == 0u) { if (xb_ld(&(bar)[XB_TMO])) break; if (_sp > XB_SPIN_CAP) { atomicAdd(&(bar)[XB_TMO], 1u); break; } } } } while (0)
; __device__ __forceinline__ void xcd_barrier(const XcdBarrier& b) {
;     ...
;         if (old + 1u == (gen + 1u) * nloc) {
;             __builtin_amdgcn_fence(__ATOMIC_RELEASE, "agent");
;             asm volatile("s_waitcnt vmcnt(0)" ::: "memory");
;             const unsigned og = xb_add(&bar[XB_TOP], 1u);
;             const unsigned tg = og / nx;
;             if (og + 1u == (tg + 1u) * nx) xb_add(&bar[XB_TOPGEN], 1u);
;             else XB_SPIN(xb_ld(&bar[XB_TOPGEN]) == tg, bar);
;             __builtin_amdgcn_fence(__ATOMIC_ACQUIRE, "agent");
;             xb_add(&bar[XB_XGEN(b.x)], 1u);
.LBB0_763:
	s_or_b64 exec, exec, s[8:9]
	v_mov_b64_e32 v[0:1], s[28:29]
	s_orn2_b64 s[8:9], s[10:11], exec
	s_branch .LBB0_764

; __device__ __forceinline__ unsigned xb_add(unsigned* p, unsigned v) { return __hip_atomic_fetch_add(p, v, __ATOMIC_RELAXED, __HIP_MEMORY_SCOPE_AGENT); }
; __device__ __forceinline__ void xcd_barrier(const XcdBarrier& b) {
;     ...
;             __builtin_amdgcn_fence(__ATOMIC_ACQUIRE, "agent");
;             xb_add(&bar[XB_XGEN(b.x)], 1u);
;             asm volatile("s_waitcnt vmcnt(0)" ::: "memory");
.LBB0_766:
	s_or_b64 exec, exec, s[6:7]
	s_mov_b64 s[6:7], exec
	v_mbcnt_lo_u32_b32 v0, s6, 0
	v_mbcnt_hi_u32_b32 v0, s7, v0
	v_cmp_eq_u32_e32 vcc, 0, v0
	s_waitcnt vmcnt(0)
	s_and_saveexec_b64 s[8:9], vcc
	s_cbranch_execz .LBB0_768
	s_bcnt1_i32_b64 s6, s[6:7]
	v_mov_b32_e32 v0, 0
	v_mov_b32_e32 v1, s6
.LBB0_768:
	s_or_b64 exec, exec, s[8:9]
	s_waitcnt vmcnt(0)

; __device__ __forceinline__ unsigned xb_add(unsigned* p, unsigned v) { return __hip_atomic_fetch_add(p, v, __ATOMIC_RELAXED, __HIP_MEMORY_SCOPE_AGENT); }
; __device__ __forceinline__ void xcd_barrier(const XcdBarrier& b) {
;     ...
;             __builtin_amdgcn_fence(__ATOMIC_ACQUIRE, "agent");
;             xb_add(&bar[XB_XGEN(b.x)], 1u);
;             asm volatile("s_waitcnt vmcnt(0)" ::: "memory");
.LBB0_843:
	s_or_b64 exec, exec, s[6:7]
	s_mov_b64 s[6:7], exec
	v_mbcnt_lo_u32_b32 v0, s6, 0
	v_mbcnt_hi_u32_b32 v0, s7, v0
	v_cmp_eq_u32_e32 vcc, 0, v0
	s_waitcnt vmcnt(0)
	s_and_saveexec_b64 s[8:9], vcc
	s_cbranch_execz .LBB0_845
	s_bcnt1_i32_b64 s6, s[6:7]
	v_mov_b32_e32 v0, 0
	v_mov_b32_e32 v1, s6
.LBB0_845:
	s_or_b64 exec, exec, s[8:9]
	s_waitcnt vmcnt(0)

; __device__ __forceinline__ unsigned xb_ld(unsigned* p)              { return __hip_atomic_load(p, __ATOMIC_RELAXED, __HIP_MEMORY_SCOPE_AGENT); }
; __device__ __forceinline__ unsigned xb_add(unsigned* p, unsigned v) { return __hip_atomic_fetch_add(p, v, __ATOMIC_RELAXED, __HIP_MEMORY_SCOPE_AGENT); }
; #define XB_SPIN(cond, bar) do { unsigned _sp = 0; while (cond) { __builtin_amdgcn_s_sleep(1); \
;     if ((++_sp & 255u) == 0u) { if (xb_ld(&(bar)[XB_TMO])) break; if (_sp > XB_SPIN_CAP) { atomicAdd(&(bar)[XB_TMO], 1u); break; } } } } while (0)
; __device__ __forceinline__ void xcd_barrier(const XcdBarrier& b) {
;     ...
;         if (old + 1u == (gen + 1u) * nloc) {
;             __builtin_amdgcn_fence(__ATOMIC_RELEASE, "agent");
;             asm volatile("s_waitcnt vmcnt(0)" ::: "memory");
;             const unsigned og = xb_add(&bar[XB_TOP], 1u);
;             const unsigned tg = og / nx;
;             if (og + 1u == (tg + 1u) * nx) xb_add(&bar[XB_TOPGEN], 1u);
;             else XB_SPIN(xb_ld(&bar[XB_TOPGEN]) == tg, bar);
;             __builtin_amdgcn_fence(__ATOMIC_ACQUIRE, "agent");
;             xb_add(&bar[XB_XGEN(b.x)], 1u);
.LBB0_945:
	s_or_b64 exec, exec, s[10:11]
	v_mov_b64_e32 v[0:1], s[28:29]
	s_orn2_b64 s[10:11], s[12:13], exec
	s_branch .LBB0_946

; __device__ __forceinline__ unsigned xb_add(unsigned* p, unsigned v) { return __hip_atomic_fetch_add(p, v, __ATOMIC_RELAXED, __HIP_MEMORY_SCOPE_AGENT); }
; __device__ __forceinline__ void xcd_barrier(const XcdBarrier& b) {
;     ...
;             __builtin_amdgcn_fence(__ATOMIC_ACQUIRE, "agent");
;             xb_add(&bar[XB_XGEN(b.x)], 1u);
;             asm volatile("s_waitcnt vmcnt(0)" ::: "memory");
.LBB0_948:
	s_or_b64 exec, exec, s[8:9]
	s_mov_b64 s[8:9], exec
	v_mbcnt_lo_u32_b32 v0, s8, 0
	v_mbcnt_hi_u32_b32 v0, s9, v0
	v_cmp_eq_u32_e32 vcc, 0, v0
	s_waitcnt vmcnt(0)
	s_and_saveexec_b64 s[10:11], vcc
	s_cbranch_execz .LBB0_950
	s_bcnt1_i32_b64 s8, s[8:9]
	v_mov_b32_e32 v0, 0
	v_mov_b32_e32 v1, s8
.LBB0_950:
	s_or_b64 exec, exec, s[10:11]
	s_waitcnt vmcnt(0)

; __device__ __forceinline__ unsigned xb_ld(unsigned* p)              { return __hip_atomic_load(p, __ATOMIC_RELAXED, __HIP_MEMORY_SCOPE_AGENT); }
; __device__ __forceinline__ unsigned xb_add(unsigned* p, unsigned v) { return __hip_atomic_fetch_add(p, v, __ATOMIC_RELAXED, __HIP_MEMORY_SCOPE_AGENT); }
; #define XB_SPIN(cond, bar) do { unsigned _sp = 0; while (cond) { __builtin_amdgcn_s_sleep(1); \
;     if ((++_sp & 255u) == 0u) { if (xb_ld(&(bar)[XB_TMO])) break; if (_sp > XB_SPIN_CAP) { atomicAdd(&(bar)[XB_TMO], 1u); break; } } } } while (0)
; __device__ __forceinline__ void xcd_barrier(const XcdBarrier& b) {
;     ...
;         if (old + 1u == (gen + 1u) * nloc) {
;             __builtin_amdgcn_fence(__ATOMIC_RELEASE, "agent");
;             asm volatile("s_waitcnt vmcnt(0)" ::: "memory");
;             const unsigned og = xb_add(&bar[XB_TOP], 1u);
;             const unsigned tg = og / nx;
;             if (og + 1u == (tg + 1u) * nx) xb_add(&bar[XB_TOPGEN], 1u);
;             else XB_SPIN(xb_ld(&bar[XB_TOPGEN]) == tg, bar);
;             __builtin_amdgcn_fence(__ATOMIC_ACQUIRE, "agent");
;             xb_add(&bar[XB_XGEN(b.x)], 1u);
.LBB0_1046:
	s_or_b64 exec, exec, s[6:7]
	v_mov_b64_e32 v[0:1], s[28:29]
	s_orn2_b64 s[6:7], s[8:9], exec
	s_branch .LBB0_1047
.Lbar_last_5:
	s_or_b64 exec, exec, s[4:5]
	v_mov_b32_e32 v2, 1
	global_atomic_add v[0:1], v2, off
	v_add_co_u32_e32 v4, vcc, 0xffffef00, v0
	s_nop 1
	v_addc_co_u32_e32 v5, vcc, -1, v1, vcc
	global_atomic_add v[4:5], v2, off
	global_atomic_add v[4:5], v2, off offset:256
	global_atomic_add v[4:5], v2, off offset:512
	global_atomic_add v[4:5], v2, off offset:768
	global_atomic_add v[4:5], v2, off offset:1024
	global_atomic_add v[4:5], v2, off offset:1280
	global_atomic_add v[4:5], v2, off offset:1536
	global_atomic_add v[4:5], v2, off offset:1792
	global_atomic_add v[4:5], v2, off offset:2048
	global_atomic_add v[4:5], v2, off offset:2304
	global_atomic_add v[4:5], v2, off offset:2560
	global_atomic_add v[4:5], v2, off offset:2816
	global_atomic_add v[4:5], v2, off offset:3072
	global_atomic_add v[4:5], v2, off offset:3328
	global_atomic_add v[4:5], v2, off offset:3584
	global_atomic_add v[4:5], v2, off offset:3840
	s_mov_b64 s[6:7], 0

; __device__ __forceinline__ unsigned xb_add(unsigned* p, unsigned v) { return __hip_atomic_fetch_add(p, v, __ATOMIC_RELAXED, __HIP_MEMORY_SCOPE_AGENT); }
; __device__ __forceinline__ void xcd_barrier(const XcdBarrier& b) {
;     ...
;             __builtin_amdgcn_fence(__ATOMIC_ACQUIRE, "agent");
;             xb_add(&bar[XB_XGEN(b.x)], 1u);
;             asm volatile("s_waitcnt vmcnt(0)" ::: "memory");
.LBB0_1049:
	s_or_b64 exec, exec, s[4:5]
	s_mov_b64 s[4:5], exec
	v_mbcnt_lo_u32_b32 v0, s4, 0
	v_mbcnt_hi_u32_b32 v0, s5, v0
	v_cmp_eq_u32_e32 vcc, 0, v0
	s_waitcnt vmcnt(0)
	s_and_saveexec_b64 s[6:7], vcc
	s_cbranch_execz .LBB0_1051
	s_bcnt1_i32_b64 s4, s[4:5]
	v_mov_b32_e32 v0, 0
	v_mov_b32_e32 v1, s4
.LBB0_1051:
	s_or_b64 exec, exec, s[6:7]
	s_waitcnt vmcnt(0)

; __device__ __forceinline__ unsigned xb_add(unsigned* p, unsigned v) { return __hip_atomic_fetch_add(p, v, __ATOMIC_RELAXED, __HIP_MEMORY_SCOPE_AGENT); }
; __device__ __forceinline__ void xcd_barrier(const XcdBarrier& b) {
;     ...
;             __builtin_amdgcn_fence(__ATOMIC_ACQUIRE, "agent");
;             xb_add(&bar[XB_XGEN(b.x)], 1u);
;             asm volatile("s_waitcnt vmcnt(0)" ::: "memory");
.LBB0_1249:
	s_or_b64 exec, exec, s[6:7]
	s_mov_b64 s[6:7], exec
	v_mbcnt_lo_u32_b32 v0, s6, 0
	v_mbcnt_hi_u32_b32 v0, s7, v0
	v_cmp_eq_u32_e32 vcc, 0, v0
	s_waitcnt vmcnt(0)
	s_and_saveexec_b64 s[8:9], vcc
	s_cbranch_execz .LBB0_1251
	s_bcnt1_i32_b64 s6, s[6:7]
	v_mov_b32_e32 v0, 0
	v_mov_b32_e32 v1, s6
.LBB0_1251:
	s_or_b64 exec, exec, s[8:9]
	s_waitcnt vmcnt(0)

; __device__ __forceinline__ unsigned xb_ld(unsigned* p)              { return __hip_atomic_load(p, __ATOMIC_RELAXED, __HIP_MEMORY_SCOPE_AGENT); }
; __device__ __forceinline__ unsigned xb_add(unsigned* p, unsigned v) { return __hip_atomic_fetch_add(p, v, __ATOMIC_RELAXED, __HIP_MEMORY_SCOPE_AGENT); }
; #define XB_SPIN(cond, bar) do { unsigned _sp = 0; while (cond) { __builtin_amdgcn_s_sleep(1); \
;     if ((++_sp & 255u) == 0u) { if (xb_ld(&(bar)[XB_TMO])) break; if (_sp > XB_SPIN_CAP) { atomicAdd(&(bar)[XB_TMO], 1u); break; } } } } while (0)
; __device__ __forceinline__ void xcd_barrier(const XcdBarrier& b) {
;     ...
;         if (old + 1u == (gen + 1u) * nloc) {
;             __builtin_amdgcn_fence(__ATOMIC_RELEASE, "agent");
;             asm volatile("s_waitcnt vmcnt(0)" ::: "memory");
;             const unsigned og = xb_add(&bar[XB_TOP], 1u);
;             const unsigned tg = og / nx;
;             if (og + 1u == (tg + 1u) * nx) xb_add(&bar[XB_TOPGEN], 1u);
;             else XB_SPIN(xb_ld(&bar[XB_TOPGEN]) == tg, bar);
;             __builtin_amdgcn_fence(__ATOMIC_ACQUIRE, "agent");
;             xb_add(&bar[XB_XGEN(b.x)], 1u);
.LBB0_1385:
	s_or_b64 exec, exec, s[4:5]
	v_mov_b64_e32 v[0:1], s[28:29]
	s_orn2_b64 s[4:5], s[6:7], exec
	s_branch .LBB0_1386
.Lbar_last_7:
	s_or_b64 exec, exec, s[2:3]
	v_mov_b32_e32 v2, 1
	global_atomic_add v[0:1], v2, off
	v_add_co_u32_e32 v4, vcc, 0xffffef00, v0
	s_nop 1
	v_addc_co_u32_e32 v5, vcc, -1, v1, vcc
	global_atomic_add v[4:5], v2, off
	global_atomic_add v[4:5], v2, off offset:256
	global_atomic_add v[4:5], v2, off offset:512
	global_atomic_add v[4:5], v2, off offset:768
	global_atomic_add v[4:5], v2, off offset:1024
	global_atomic_add v[4:5], v2, off offset:1280
	global_atomic_add v[4:5], v2, off offset:1536
	global_atomic_add v[4:5], v2, off offset:1792
	global_atomic_add v[4:5], v2, off offset:2048
	global_atomic_add v[4:5], v2, off offset:2304
	global_atomic_add v[4:5], v2, off offset:2560
	global_atomic_add v[4:5], v2, off offset:2816
	global_atomic_add v[4:5], v2, off offset:3072
	global_atomic_add v[4:5], v2, off offset:3328
	global_atomic_add v[4:5], v2, off offset:3584
	global_atomic_add v[4:5], v2, off offset:3840
	s_mov_b64 s[4:5], 0

; __device__ __forceinline__ unsigned xb_add(unsigned* p, unsigned v) { return __hip_atomic_fetch_add(p, v, __ATOMIC_RELAXED, __HIP_MEMORY_SCOPE_AGENT); }
; __device__ __forceinline__ void xcd_barrier(const XcdBarrier& b) {
;     ...
;             __builtin_amdgcn_fence(__ATOMIC_ACQUIRE, "agent");
;             xb_add(&bar[XB_XGEN(b.x)], 1u);
;             asm volatile("s_waitcnt vmcnt(0)" ::: "memory");
.LBB0_1388:
	s_or_b64 exec, exec, s[2:3]
	s_mov_b64 s[2:3], exec
	v_mbcnt_lo_u32_b32 v0, s2, 0
	v_mbcnt_hi_u32_b32 v0, s3, v0
	v_cmp_eq_u32_e32 vcc, 0, v0
	s_waitcnt vmcnt(0)
	s_and_saveexec_b64 s[4:5], vcc
	s_cbranch_execz .LBB0_1390
	s_bcnt1_i32_b64 s2, s[2:3]
	v_mov_b32_e32 v0, 0
	v_mov_b32_e32 v1, s2
.LBB0_1390:
	s_or_b64 exec, exec, s[4:5]
	s_waitcnt vmcnt(0)
